# static priority raise for the SSD scan wave while it computes the next step's scan (on top of the M-block raise)
# baseline (speedup 1.0000x reference)
.LBB0_35:
	s_mov_b32 s44, 0
	s_add_i32 s2, s44, s76
	s_waitcnt vmcnt(0)
	v_mbcnt_lo_u32_b32 v0, -1, 0
	v_mbcnt_hi_u32_b32 v0, -1, v0
	s_add_i32 s18, s44, s69
	v_lshl_add_u32 v176, s2, 6, v0
	s_add_i32 s82, s44, s72
	v_readfirstlane_b32 s2, v176
	s_ashr_i32 s6, s2, 6
	v_readlane_b32 s4, v254, 11
	s_cmp_gt_u32 s4, 16
	s_cselect_b64 s[2:3], -1, 0
	s_cmp_lt_u32 s4, 17
	s_cselect_b64 s[10:11], -1, 0
	s_and_b64 s[4:5], s[10:11], exec
	s_mov_b32 s4, 0x12000
	s_cselect_b32 s4, s4, 0x10000
	s_lshl_b32 s5, s82, 3
	s_abs_i32 s7, s5
	v_cvt_f32_u32_e32 v1, s7
	s_mov_b32 s14, s18
	v_writelane_b32 v254, s14, 41
	s_lshl_b32 s13, s18, 3
	v_rcp_iflag_f32_e32 v1, v1
	v_writelane_b32 v254, s15, 42
	s_add_i32 s6, s6, s13
	s_sub_i32 s13, 0, s7
	v_mul_f32_e32 v1, 0x4f7ffffe, v1
	v_cvt_u32_f32_e32 v1, v1
	s_add_i32 s12, s4, s5
	s_add_i32 s12, s12, -1
	s_xor_b32 s5, s12, s5
	v_readfirstlane_b32 s14, v1
	s_mul_i32 s13, s13, s14
	s_mul_hi_u32 s13, s14, s13
	s_abs_i32 s12, s12
	s_add_i32 s14, s14, s13
	s_mul_hi_u32 s13, s12, s14
	s_mul_i32 s14, s13, s7
	s_sub_i32 s12, s12, s14
	s_ashr_i32 s5, s5, 31
	s_add_i32 s14, s13, 1
	s_sub_i32 s15, s12, s7
	s_cmp_ge_u32 s12, s7
	s_cselect_b32 s13, s14, s13
	s_cselect_b32 s12, s15, s12
	s_add_i32 s14, s13, 1
	s_cmp_ge_u32 s12, s7
	s_cselect_b32 s7, s14, s13
	s_xor_b32 s7, s7, s5
	s_sub_i32 s5, s7, s5
	s_mul_i32 s56, s5, s6
	s_add_i32 s5, s56, s5
	s_min_i32 s57, s5, s4
	s_cmp_ge_i32 s56, s57
	s_mov_b32 s54, 0x800000
	s_cbranch_scc1 .LBB0_134
	v_readlane_b32 s28, v254, 11
	s_cmp_lg_u32 s28, 21
	s_cselect_b64 s[6:7], -1, 0
	s_cmp_eq_u32 s28, 21
	s_cselect_b64 s[12:13], -1, 0
	s_cmp_eq_u32 s28, 17
	s_cselect_b64 s[14:15], -1, 0
	s_lshl_b64 s[4:5], s[44:45], 3
	s_add_u32 s22, s70, s4
	v_readlane_b32 s24, v253, 62
	s_addc_u32 s23, s71, s5
	v_readlane_b32 s26, v254, 0
	v_readlane_b32 s27, v254, 1
	s_add_u32 s4, s26, s44
	s_addc_u32 s5, s27, 0
	s_lshl_b64 s[18:19], s[44:45], 2
	v_readlane_b32 s25, v253, 63
	s_add_u32 s58, s24, s18
	s_addc_u32 s59, s25, s19
	s_cmp_eq_u32 s28, 10
	s_cselect_b64 s[18:19], -1, 0
	s_and_b64 s[20:21], s[18:19], exec
	s_movk_i32 s20, 0x400
	s_cselect_b32 s60, s20, 0x1000
	s_cselect_b32 s61, 0, 0xc00
	s_or_b64 s[12:13], s[18:19], s[12:13]
	s_and_b64 s[18:19], s[12:13], exec
	s_cselect_b32 s18, 64, 48
	s_add_u32 s18, s22, s18
	s_addc_u32 s19, s23, 0
	s_load_dwordx2 s[18:19], s[18:19], 0x0
	s_and_b64 s[10:11], s[10:11], exec
	s_cselect_b32 s20, 0, 0x1000
	v_and_b32_e32 v34, 63, v0
	v_lshlrev_b32_e32 v192, 5, v34
	s_waitcnt lgkmcnt(0)
	s_add_u32 s10, s18, s20
	s_addc_u32 s11, s19, 0
	s_and_b64 s[12:13], s[12:13], exec
	s_cselect_b32 s12, 0x48, 56
	s_add_u32 s12, s22, s12
	s_addc_u32 s13, s23, 0
	s_load_dwordx2 s[12:13], s[12:13], 0x0
	v_xor_b32_e32 v32, 1, v229
	v_cmp_lt_i32_e32 vcc, v32, v231
	v_mov_b32_e32 v33, v193
	v_mov_b32_e32 v62, 0
	s_waitcnt lgkmcnt(0)
	s_add_u32 s12, s12, s20
	s_addc_u32 s13, s13, 0
	global_load_dwordx4 v[0:3], v192, s[10:11] offset:16
	global_load_dwordx4 v[4:7], v192, s[10:11]
	global_load_dwordx4 v[8:11], v192, s[12:13] offset:16
	global_load_dwordx4 v[12:15], v192, s[12:13]
	global_load_dwordx4 v[16:19], v192, s[10:11] offset:2064
	global_load_dwordx4 v[20:23], v192, s[10:11] offset:2048
	global_load_dwordx4 v[24:27], v192, s[12:13] offset:2064
	global_load_dwordx4 v[28:31], v192, s[12:13] offset:2048
	v_cndmask_b32_e32 v32, v229, v32, vcc
	v_lshlrev_b32_e32 v109, 2, v32
	v_xor_b32_e32 v32, 2, v229
	v_cmp_lt_i32_e32 vcc, v32, v231
	s_cmp_eq_u32 s28, 6
	s_cselect_b64 s[10:11], -1, 0
	v_cndmask_b32_e32 v32, v229, v32, vcc
	v_lshlrev_b32_e32 v121, 2, v32
	v_xor_b32_e32 v32, 4, v229
	v_cmp_lt_i32_e32 vcc, v32, v231
	s_and_b64 s[12:13], s[10:11], exec
	s_mov_b32 s12, 0x44d4000
	v_cndmask_b32_e32 v32, v229, v32, vcc
	v_lshlrev_b32_e32 v122, 2, v32
	v_xor_b32_e32 v32, 8, v229
	v_cmp_lt_i32_e32 vcc, v32, v231
	s_cselect_b32 s12, s12, 0x459a000
	s_or_b64 s[10:11], s[10:11], s[14:15]
	v_cndmask_b32_e32 v32, v229, v32, vcc
	v_lshlrev_b32_e32 v123, 2, v32
	v_xor_b32_e32 v32, 16, v229
	v_cmp_lt_i32_e32 vcc, v32, v231
	s_add_u32 s62, s4, 0x38260000
	s_addc_u32 s63, s5, 0
	v_cndmask_b32_e32 v32, v229, v32, vcc
	v_lshlrev_b32_e32 v124, 2, v32
	v_xor_b32_e32 v32, 32, v229
	s_add_u32 s64, s4, 0x3d2e4000
	v_cmp_lt_i32_e32 vcc, v32, v231
	s_addc_u32 s65, s5, 0
	s_add_u32 s14, s4, s12
	v_cndmask_b32_e32 v32, v229, v32, vcc
	v_lshlrev_b32_e32 v125, 2, v32
	v_lshlrev_b32_e32 v32, 4, v34
	s_addc_u32 s15, s5, 0
	v_lshl_add_u64 v[32:33], s[4:5], 0, v[32:33]
	s_mov_b64 s[4:5], 0x4660000
	v_lshl_add_u64 v[110:111], v[32:33], 0, s[4:5]
	v_cmp_eq_u32_e32 vcc, 0, v34
	s_mov_b64 s[4:5], 0x16660000
	v_lshlrev_b32_e32 v108, 3, v34
	s_mov_b32 s68, -1
	s_and_b64 s[12:13], s[6:7], vcc
	v_lshl_add_u64 v[112:113], s[14:15], 0, v[192:193]
	v_lshl_add_u64 v[114:115], v[32:33], 0, s[4:5]
	v_mov_b32_e32 v63, v62
	v_mov_b32_e32 v54, v62
	v_mov_b32_e32 v55, v62
	v_mov_b32_e32 v60, v62
	v_mov_b32_e32 v61, v62
	v_mov_b32_e32 v52, v62
	v_mov_b32_e32 v53, v62
	v_mov_b32_e32 v58, v62
	v_mov_b32_e32 v59, v62
	v_mov_b32_e32 v50, v62
	v_mov_b32_e32 v51, v62
	v_mov_b32_e32 v56, v62
	v_mov_b32_e32 v57, v62
	v_mov_b32_e32 v48, v62
	v_mov_b32_e32 v49, v62
	v_mov_b32_e32 v38, v62
	v_mov_b32_e32 v39, v62
	v_mov_b32_e32 v46, v62
	v_mov_b32_e32 v47, v62
	v_mov_b32_e32 v36, v62
	v_mov_b32_e32 v37, v62
	v_mov_b32_e32 v44, v62
	v_mov_b32_e32 v45, v62
	v_mov_b32_e32 v34, v62
	v_mov_b32_e32 v35, v62
	v_mov_b32_e32 v42, v62
	v_mov_b32_e32 v43, v62
	v_mov_b32_e32 v32, v62
	v_mov_b32_e32 v33, v62
	v_mov_b32_e32 v40, v62
	v_mov_b32_e32 v41, v62
	s_branch .LBB0_38
	s_nop 0
	s_nop 0
	s_nop 0
	s_nop 0
	s_nop 0
	s_nop 0
	s_nop 0
.LBB0_37:
	s_add_i32 s56, s56, 4
	s_cmp_ge_i32 s56, s57
	s_cbranch_scc1 .LBB0_134

.LBB0_223:
	s_waitcnt lgkmcnt(0)
	s_barrier
	s_and_b64 vcc, exec, s[0:1]
	s_cbranch_vccz .Lscan_ret1
	s_add_i32 s98, s73, 1
	s_cmp_gt_u32 s98, 17
	s_cbranch_scc1 .Lscan_ret1
	s_cmp_gt_u32 s98, 1
	s_cselect_b32 s99, 19, 1
	s_sub_i32 s99, s99, s98
	s_and_b64 s[100:101], s[30:31], exec
	s_cselect_b32 s98, s98, s99
	s_lshl_b32 s98, s98, 7
	s_add_u32 s98, s75, s98
	s_addc_u32 s99, s74, 0
	s_mov_b32 s101, 1
	s_setprio 1
	s_branch .Lscan_block
.Lscan_ret1:
	s_setprio 0
	s_and_saveexec_b64 s[64:65], s[36:37]
	s_cbranch_execz .LBB0_218
